# K-loops: the compiler-artifact wait between the B and A LDS read groups of the first super-phase relaxed from lgkmcnt(0) to lgkmcnt(4)
# baseline (speedup 1.0000x reference)
.LBB0_318:
	v_add_u32_e32 v128, 0x10000, v251
	ds_read_b128 v[146:149], v128
	ds_read_b128 v[150:153], v128 offset:1024
	ds_read_b128 v[154:157], v128 offset:2048
	ds_read_b128 v[158:161], v128 offset:3072
	v_add_u32_e32 v128, 0x14000, v251
	ds_read_b128 v[130:133], v128
	ds_read_b128 v[134:137], v128 offset:1024
	ds_read_b128 v[138:141], v128 offset:2048
	ds_read_b128 v[142:145], v128 offset:3072
	s_cmp_eq_u32 s57, s3
	s_cselect_b32 s73, s55, s94
	s_cselect_b32 s72, s54, s93
	s_cselect_b32 s77, s63, s92
	s_cselect_b32 s76, s62, s8
	s_waitcnt lgkmcnt(4)
	ds_read_b128 v[162:165], v252
	ds_read_b128 v[166:169], v252 offset:1024
	ds_read_b128 v[170:173], v252 offset:2048
	ds_read_b128 v[174:177], v252 offset:3072
	ds_read_b128 v[178:181], v252 offset:4096
	ds_read_b128 v[182:185], v252 offset:5120
	ds_read_b128 v[186:189], v252 offset:6144
	ds_read_b128 v[190:193], v252 offset:7168
	s_add_u32 s42, s93, s9
	s_addc_u32 s43, s94, 0
	s_add_u32 s42, s42, 0xffffff80
	s_addc_u32 s43, s43, -1
	s_mov_b32 s74, m0
	s_mov_b32 m0, s65
	s_nop 0
	global_load_lds_dwordx4 v245, s[42:43]
	s_mov_b32 m0, s74
	s_nop 0
	s_mov_b32 s74, m0
	s_mov_b32 m0, s66
	s_nop 0
	global_load_lds_dwordx4 v247, s[42:43]
	s_mov_b32 m0, s74
	s_waitcnt vmcnt(8)
	s_waitcnt lgkmcnt(0)
	s_barrier
	s_setprio 1
	s_waitcnt lgkmcnt(0)
	v_mfma_f32_16x16x32_bf16 v[124:127], v[146:149], v[162:165], v[124:127]
	v_mfma_f32_16x16x32_bf16 v[120:123], v[154:157], v[162:165], v[120:123]
	v_mfma_f32_16x16x32_bf16 v[108:111], v[146:149], v[170:173], v[108:111]
	v_mfma_f32_16x16x32_bf16 v[104:107], v[154:157], v[170:173], v[104:107]
	v_mfma_f32_16x16x32_bf16 v[92:95], v[146:149], v[178:181], v[92:95]
	v_mfma_f32_16x16x32_bf16 v[88:91], v[154:157], v[178:181], v[88:91]
	v_mfma_f32_16x16x32_bf16 v[76:79], v[146:149], v[186:189], v[76:79]
	v_mfma_f32_16x16x32_bf16 v[72:75], v[154:157], v[186:189], v[72:75]
	v_mfma_f32_16x16x32_bf16 v[124:127], v[150:153], v[166:169], v[124:127]
	v_mfma_f32_16x16x32_bf16 v[120:123], v[158:161], v[166:169], v[120:123]
	v_mfma_f32_16x16x32_bf16 v[108:111], v[150:153], v[174:177], v[108:111]
	v_mfma_f32_16x16x32_bf16 v[104:107], v[158:161], v[174:177], v[104:107]
	v_mfma_f32_16x16x32_bf16 v[92:95], v[150:153], v[182:185], v[92:95]
	v_mfma_f32_16x16x32_bf16 v[88:91], v[158:161], v[182:185], v[88:91]
	v_mfma_f32_16x16x32_bf16 v[76:79], v[150:153], v[190:193], v[76:79]
	v_mfma_f32_16x16x32_bf16 v[72:75], v[158:161], v[190:193], v[72:75]
	s_setprio 0
	s_setprio 1
	v_mfma_f32_16x16x32_bf16 v[116:119], v[130:133], v[162:165], v[116:119]
	v_mfma_f32_16x16x32_bf16 v[112:115], v[138:141], v[162:165], v[112:115]
	v_mfma_f32_16x16x32_bf16 v[100:103], v[130:133], v[170:173], v[100:103]
	v_mfma_f32_16x16x32_bf16 v[96:99], v[138:141], v[170:173], v[96:99]
	v_mfma_f32_16x16x32_bf16 v[84:87], v[130:133], v[178:181], v[84:87]
	v_mfma_f32_16x16x32_bf16 v[80:83], v[138:141], v[178:181], v[80:83]
	v_mfma_f32_16x16x32_bf16 v[68:71], v[130:133], v[186:189], v[68:71]
	v_mfma_f32_16x16x32_bf16 v[64:67], v[138:141], v[186:189], v[64:67]
	v_mfma_f32_16x16x32_bf16 v[116:119], v[134:137], v[166:169], v[116:119]
	v_mfma_f32_16x16x32_bf16 v[112:115], v[142:145], v[166:169], v[112:115]
	v_mfma_f32_16x16x32_bf16 v[100:103], v[134:137], v[174:177], v[100:103]
	v_mfma_f32_16x16x32_bf16 v[96:99], v[142:145], v[174:177], v[96:99]
	v_mfma_f32_16x16x32_bf16 v[84:87], v[134:137], v[182:185], v[84:87]
	v_mfma_f32_16x16x32_bf16 v[80:83], v[142:145], v[182:185], v[80:83]
	v_mfma_f32_16x16x32_bf16 v[68:71], v[134:137], v[190:193], v[68:71]
	v_mfma_f32_16x16x32_bf16 v[64:67], v[142:145], v[190:193], v[64:67]
	s_setprio 0
	s_barrier
	s_mov_b32 s42, m0
	s_mov_b32 m0, s14
	s_nop 0
	global_load_lds_dwordx4 v246, s[76:77]
	s_mov_b32 m0, s42
	ds_read_b128 v[186:189], v252 offset:16384
	ds_read_b128 v[190:193], v252 offset:17408
	s_add_u32 s74, s76, s9
	s_mov_b32 s42, m0
	s_mov_b32 m0, s15
	s_nop 0
	global_load_lds_dwordx4 v248, s[76:77]
	s_mov_b32 m0, s42
	ds_read_b128 v[178:181], v252 offset:18432
	ds_read_b128 v[182:185], v252 offset:19456
	s_addc_u32 s75, s77, 0
	s_mov_b32 s42, m0
	s_mov_b32 m0, s16
	s_nop 0
	global_load_lds_dwordx4 v246, s[74:75]
	s_mov_b32 m0, s42
	ds_read_b128 v[170:173], v252 offset:20480
	ds_read_b128 v[174:177], v252 offset:21504
	v_cndmask_b32_e64 v128, 0, 1, s[68:69]
	s_mov_b32 s42, m0
	s_mov_b32 m0, s17
	s_nop 0
	global_load_lds_dwordx4 v248, s[74:75]
	s_mov_b32 m0, s42
	ds_read_b128 v[162:165], v252 offset:22528
	ds_read_b128 v[166:169], v252 offset:23552
	s_andn2_b64 vcc, exec, s[68:69]
	s_mov_b32 s42, m0
	s_mov_b32 m0, s11
	s_nop 0
	global_load_lds_dwordx4 v245, s[72:73]
	s_mov_b32 m0, s42
	s_nop 0
	s_mov_b32 s42, m0
	s_mov_b32 m0, s19
	s_nop 0
	global_load_lds_dwordx4 v247, s[72:73]
	s_mov_b32 m0, s42
	s_waitcnt vmcnt(8)
	s_waitcnt lgkmcnt(0)
	s_barrier
	v_cmp_ne_u32_e64 s[42:43], 1, v128
	s_cbranch_vccnz .LBB0_320
	s_setprio 1
	s_waitcnt lgkmcnt(0)
	v_mfma_f32_16x16x32_bf16 v[60:63], v[146:149], v[186:189], v[60:63]
	v_mfma_f32_16x16x32_bf16 v[56:59], v[154:157], v[186:189], v[56:59]
	v_mfma_f32_16x16x32_bf16 v[44:47], v[146:149], v[178:181], v[44:47]
	v_mfma_f32_16x16x32_bf16 v[40:43], v[154:157], v[178:181], v[40:43]
	v_mfma_f32_16x16x32_bf16 v[28:31], v[146:149], v[170:173], v[28:31]
	v_mfma_f32_16x16x32_bf16 v[24:27], v[154:157], v[170:173], v[24:27]
	v_mfma_f32_16x16x32_bf16 v[12:15], v[146:149], v[162:165], v[12:15]
	v_mfma_f32_16x16x32_bf16 v[8:11], v[154:157], v[162:165], v[8:11]
	v_mfma_f32_16x16x32_bf16 v[60:63], v[150:153], v[190:193], v[60:63]
	v_mfma_f32_16x16x32_bf16 v[56:59], v[158:161], v[190:193], v[56:59]
	v_mfma_f32_16x16x32_bf16 v[44:47], v[150:153], v[182:185], v[44:47]
	v_mfma_f32_16x16x32_bf16 v[40:43], v[158:161], v[182:185], v[40:43]
	v_mfma_f32_16x16x32_bf16 v[28:31], v[150:153], v[174:177], v[28:31]
	v_mfma_f32_16x16x32_bf16 v[24:27], v[158:161], v[174:177], v[24:27]
	v_mfma_f32_16x16x32_bf16 v[12:15], v[150:153], v[166:169], v[12:15]
	v_mfma_f32_16x16x32_bf16 v[8:11], v[158:161], v[166:169], v[8:11]
	s_setprio 0
	s_setprio 1
	v_mfma_f32_16x16x32_bf16 v[52:55], v[130:133], v[186:189], v[52:55]
	v_mfma_f32_16x16x32_bf16 v[48:51], v[138:141], v[186:189], v[48:51]
	v_mfma_f32_16x16x32_bf16 v[36:39], v[130:133], v[178:181], v[36:39]
	v_mfma_f32_16x16x32_bf16 v[32:35], v[138:141], v[178:181], v[32:35]
	v_mfma_f32_16x16x32_bf16 v[20:23], v[130:133], v[170:173], v[20:23]
	v_mfma_f32_16x16x32_bf16 v[16:19], v[138:141], v[170:173], v[16:19]
	v_mfma_f32_16x16x32_bf16 v[4:7], v[130:133], v[162:165], v[4:7]
	v_mfma_f32_16x16x32_bf16 v[0:3], v[138:141], v[162:165], v[0:3]
	v_mfma_f32_16x16x32_bf16 v[52:55], v[134:137], v[190:193], v[52:55]
	v_mfma_f32_16x16x32_bf16 v[48:51], v[142:145], v[190:193], v[48:51]
	v_mfma_f32_16x16x32_bf16 v[36:39], v[134:137], v[182:185], v[36:39]
	v_mfma_f32_16x16x32_bf16 v[32:35], v[142:145], v[182:185], v[32:35]
	v_mfma_f32_16x16x32_bf16 v[20:23], v[134:137], v[174:177], v[20:23]
	v_mfma_f32_16x16x32_bf16 v[16:19], v[142:145], v[174:177], v[16:19]
	v_mfma_f32_16x16x32_bf16 v[4:7], v[134:137], v[166:169], v[4:7]
	v_mfma_f32_16x16x32_bf16 v[0:3], v[142:145], v[166:169], v[0:3]
	s_setprio 0
.LBB0_320:
	s_add_u32 s80, s72, 0x80
	s_addc_u32 s81, s73, 0
	s_add_u32 s76, s76, 0x80
	s_addc_u32 s77, s77, 0
	s_barrier
	v_add_u32_e32 v128, 0x18000, v251
	ds_read_b128 v[146:149], v128
	ds_read_b128 v[150:153], v128 offset:1024
	ds_read_b128 v[154:157], v128 offset:2048
	ds_read_b128 v[158:161], v128 offset:3072
	v_add_u32_e32 v128, 0x1c000, v251
	ds_read_b128 v[130:133], v128
	ds_read_b128 v[134:137], v128 offset:1024
	ds_read_b128 v[138:141], v128 offset:2048
	ds_read_b128 v[142:145], v128 offset:3072
	s_waitcnt lgkmcnt(4)
	ds_read_b128 v[162:165], v252 offset:32768
	ds_read_b128 v[166:169], v252 offset:33792
	ds_read_b128 v[170:173], v252 offset:34816
	ds_read_b128 v[174:177], v252 offset:35840
	ds_read_b128 v[178:181], v252 offset:36864
	ds_read_b128 v[182:185], v252 offset:37888
	ds_read_b128 v[186:189], v252 offset:38912
	ds_read_b128 v[190:193], v252 offset:39936
	s_add_u32 s72, s72, s9
	s_addc_u32 s73, s73, 0
	s_mov_b32 s95, m0
	s_mov_b32 m0, s20
	s_nop 0
	global_load_lds_dwordx4 v245, s[72:73]
	s_mov_b32 m0, s95
	s_nop 0
	s_mov_b32 s95, m0
	s_mov_b32 m0, s21
	s_nop 0
	global_load_lds_dwordx4 v247, s[72:73]
	s_mov_b32 m0, s95
	s_waitcnt vmcnt(8)
	s_waitcnt lgkmcnt(0)
	s_barrier
	s_setprio 1
	s_waitcnt lgkmcnt(0)
	v_mfma_f32_16x16x32_bf16 v[124:127], v[146:149], v[162:165], v[124:127]
	v_mfma_f32_16x16x32_bf16 v[120:123], v[154:157], v[162:165], v[120:123]
	v_mfma_f32_16x16x32_bf16 v[108:111], v[146:149], v[170:173], v[108:111]
	v_mfma_f32_16x16x32_bf16 v[104:107], v[154:157], v[170:173], v[104:107]
	v_mfma_f32_16x16x32_bf16 v[92:95], v[146:149], v[178:181], v[92:95]
	v_mfma_f32_16x16x32_bf16 v[88:91], v[154:157], v[178:181], v[88:91]
	v_mfma_f32_16x16x32_bf16 v[76:79], v[146:149], v[186:189], v[76:79]
	v_mfma_f32_16x16x32_bf16 v[72:75], v[154:157], v[186:189], v[72:75]
	v_mfma_f32_16x16x32_bf16 v[124:127], v[150:153], v[166:169], v[124:127]
	v_mfma_f32_16x16x32_bf16 v[120:123], v[158:161], v[166:169], v[120:123]
	v_mfma_f32_16x16x32_bf16 v[108:111], v[150:153], v[174:177], v[108:111]
	v_mfma_f32_16x16x32_bf16 v[104:107], v[158:161], v[174:177], v[104:107]
	v_mfma_f32_16x16x32_bf16 v[92:95], v[150:153], v[182:185], v[92:95]
	v_mfma_f32_16x16x32_bf16 v[88:91], v[158:161], v[182:185], v[88:91]
	v_mfma_f32_16x16x32_bf16 v[76:79], v[150:153], v[190:193], v[76:79]
	v_mfma_f32_16x16x32_bf16 v[72:75], v[158:161], v[190:193], v[72:75]
	s_setprio 0
	s_setprio 1
	v_mfma_f32_16x16x32_bf16 v[116:119], v[130:133], v[162:165], v[116:119]
	v_mfma_f32_16x16x32_bf16 v[112:115], v[138:141], v[162:165], v[112:115]
	v_mfma_f32_16x16x32_bf16 v[100:103], v[130:133], v[170:173], v[100:103]
	v_mfma_f32_16x16x32_bf16 v[96:99], v[138:141], v[170:173], v[96:99]
	v_mfma_f32_16x16x32_bf16 v[84:87], v[130:133], v[178:181], v[84:87]
	v_mfma_f32_16x16x32_bf16 v[80:83], v[138:141], v[178:181], v[80:83]
	v_mfma_f32_16x16x32_bf16 v[68:71], v[130:133], v[186:189], v[68:71]
	v_mfma_f32_16x16x32_bf16 v[64:67], v[138:141], v[186:189], v[64:67]
	v_mfma_f32_16x16x32_bf16 v[116:119], v[134:137], v[166:169], v[116:119]
	v_mfma_f32_16x16x32_bf16 v[112:115], v[142:145], v[166:169], v[112:115]
	v_mfma_f32_16x16x32_bf16 v[100:103], v[134:137], v[174:177], v[100:103]
	v_mfma_f32_16x16x32_bf16 v[96:99], v[142:145], v[174:177], v[96:99]
	v_mfma_f32_16x16x32_bf16 v[84:87], v[134:137], v[182:185], v[84:87]
	v_mfma_f32_16x16x32_bf16 v[80:83], v[142:145], v[182:185], v[80:83]
	v_mfma_f32_16x16x32_bf16 v[68:71], v[134:137], v[190:193], v[68:71]
	v_mfma_f32_16x16x32_bf16 v[64:67], v[142:145], v[190:193], v[64:67]
	s_setprio 0
	s_barrier
	s_mov_b32 s72, m0
	s_mov_b32 m0, s23
	s_nop 0
	global_load_lds_dwordx4 v246, s[76:77]
	s_mov_b32 m0, s72
	ds_read_b128 v[186:189], v252 offset:49152
	ds_read_b128 v[190:193], v252 offset:50176
	s_nop 0
	s_mov_b32 s72, m0
	s_mov_b32 m0, s30
	s_nop 0
	global_load_lds_dwordx4 v248, s[76:77]
	s_mov_b32 m0, s72
	ds_read_b128 v[178:181], v252 offset:51200
	ds_read_b128 v[182:185], v252 offset:52224
	s_add_u32 s72, s74, 0x80
	s_addc_u32 s73, s75, 0
	s_mov_b32 s74, m0
	s_mov_b32 m0, s52
	s_nop 0
	global_load_lds_dwordx4 v246, s[72:73]
	s_mov_b32 m0, s74
	ds_read_b128 v[170:173], v252 offset:53248
	ds_read_b128 v[174:177], v252 offset:54272
	s_and_b64 vcc, exec, s[42:43]
	s_mov_b32 s74, m0
	s_mov_b32 m0, s53
	s_nop 0
	global_load_lds_dwordx4 v248, s[72:73]
	s_mov_b32 m0, s74
	ds_read_b128 v[162:165], v252 offset:55296
	ds_read_b128 v[166:169], v252 offset:56320
	s_mov_b32 s72, m0
	s_mov_b32 m0, s47
	s_nop 0
	global_load_lds_dwordx4 v245, s[80:81]
	s_mov_b32 m0, s72
	s_nop 0
	s_mov_b32 s72, m0
	s_mov_b32 m0, s50
	s_nop 0
	global_load_lds_dwordx4 v247, s[80:81]
	s_mov_b32 m0, s72
	s_waitcnt vmcnt(8)
	s_waitcnt lgkmcnt(0)
	s_barrier
	s_cbranch_vccnz .LBB0_317
	s_setprio 1
	s_waitcnt lgkmcnt(0)
	v_mfma_f32_16x16x32_bf16 v[60:63], v[146:149], v[186:189], v[60:63]
	v_mfma_f32_16x16x32_bf16 v[56:59], v[154:157], v[186:189], v[56:59]
	v_mfma_f32_16x16x32_bf16 v[44:47], v[146:149], v[178:181], v[44:47]
	v_mfma_f32_16x16x32_bf16 v[40:43], v[154:157], v[178:181], v[40:43]
	v_mfma_f32_16x16x32_bf16 v[28:31], v[146:149], v[170:173], v[28:31]
	v_mfma_f32_16x16x32_bf16 v[24:27], v[154:157], v[170:173], v[24:27]
	v_mfma_f32_16x16x32_bf16 v[12:15], v[146:149], v[162:165], v[12:15]
	v_mfma_f32_16x16x32_bf16 v[8:11], v[154:157], v[162:165], v[8:11]
	v_mfma_f32_16x16x32_bf16 v[60:63], v[150:153], v[190:193], v[60:63]
	v_mfma_f32_16x16x32_bf16 v[56:59], v[158:161], v[190:193], v[56:59]
	v_mfma_f32_16x16x32_bf16 v[44:47], v[150:153], v[182:185], v[44:47]
	v_mfma_f32_16x16x32_bf16 v[40:43], v[158:161], v[182:185], v[40:43]
	v_mfma_f32_16x16x32_bf16 v[28:31], v[150:153], v[174:177], v[28:31]
	v_mfma_f32_16x16x32_bf16 v[24:27], v[158:161], v[174:177], v[24:27]
	v_mfma_f32_16x16x32_bf16 v[12:15], v[150:153], v[166:169], v[12:15]
	v_mfma_f32_16x16x32_bf16 v[8:11], v[158:161], v[166:169], v[8:11]
	s_setprio 0
	s_setprio 1
	v_mfma_f32_16x16x32_bf16 v[52:55], v[130:133], v[186:189], v[52:55]
	v_mfma_f32_16x16x32_bf16 v[48:51], v[138:141], v[186:189], v[48:51]
	v_mfma_f32_16x16x32_bf16 v[36:39], v[130:133], v[178:181], v[36:39]
	v_mfma_f32_16x16x32_bf16 v[32:35], v[138:141], v[178:181], v[32:35]
	v_mfma_f32_16x16x32_bf16 v[20:23], v[130:133], v[170:173], v[20:23]
	v_mfma_f32_16x16x32_bf16 v[16:19], v[138:141], v[170:173], v[16:19]
	v_mfma_f32_16x16x32_bf16 v[4:7], v[130:133], v[162:165], v[4:7]
	v_mfma_f32_16x16x32_bf16 v[0:3], v[138:141], v[162:165], v[0:3]
	v_mfma_f32_16x16x32_bf16 v[52:55], v[134:137], v[190:193], v[52:55]
	v_mfma_f32_16x16x32_bf16 v[48:51], v[142:145], v[190:193], v[48:51]
	v_mfma_f32_16x16x32_bf16 v[36:39], v[134:137], v[182:185], v[36:39]
	v_mfma_f32_16x16x32_bf16 v[32:35], v[142:145], v[182:185], v[32:35]
	v_mfma_f32_16x16x32_bf16 v[20:23], v[134:137], v[174:177], v[20:23]
	v_mfma_f32_16x16x32_bf16 v[16:19], v[142:145], v[174:177], v[16:19]
	v_mfma_f32_16x16x32_bf16 v[4:7], v[134:137], v[166:169], v[4:7]
	v_mfma_f32_16x16x32_bf16 v[0:3], v[142:145], v[166:169], v[0:3]
	s_setprio 0
	s_branch .LBB0_317

.LBB0_413:
	v_add_u32_e32 v128, 0x10000, v208
	ds_read_b128 v[146:149], v128
	ds_read_b128 v[150:153], v128 offset:1024
	ds_read_b128 v[154:157], v128 offset:2048
	ds_read_b128 v[158:161], v128 offset:3072
	v_add_u32_e32 v128, 0x14000, v208
	ds_read_b128 v[130:133], v128
	ds_read_b128 v[134:137], v128 offset:1024
	ds_read_b128 v[138:141], v128 offset:2048
	ds_read_b128 v[142:145], v128 offset:3072
	s_add_u32 s38, s46, 0xfffc0080
	s_addc_u32 s39, s47, -1
	s_cmp_eq_u32 s19, 12
	s_cselect_b32 s75, s27, s39
	s_cselect_b32 s74, s99, s38
	s_cselect_b32 s63, s23, s18
	s_cselect_b32 s62, s3, s8
	s_waitcnt lgkmcnt(4)
	ds_read_b128 v[162:165], v209
	ds_read_b128 v[166:169], v209 offset:1024
	ds_read_b128 v[170:173], v209 offset:2048
	ds_read_b128 v[174:177], v209 offset:3072
	ds_read_b128 v[178:181], v209 offset:4096
	ds_read_b128 v[182:185], v209 offset:5120
	ds_read_b128 v[186:189], v209 offset:6144
	ds_read_b128 v[190:193], v209 offset:7168
	s_mov_b32 s38, m0
	s_mov_b32 m0, s30
	s_nop 0
	global_load_lds_dwordx4 v195, s[46:47]
	s_mov_b32 m0, s38
	s_nop 0
	s_mov_b32 s38, m0
	s_mov_b32 m0, s14
	s_nop 0
	global_load_lds_dwordx4 v197, s[46:47]
	s_mov_b32 m0, s38
	s_waitcnt vmcnt(8)
	s_waitcnt lgkmcnt(0)
	s_barrier
	s_setprio 1
	s_waitcnt lgkmcnt(0)
	v_mfma_f32_16x16x32_bf16 v[124:127], v[146:149], v[162:165], v[124:127]
	v_mfma_f32_16x16x32_bf16 v[120:123], v[154:157], v[162:165], v[120:123]
	v_mfma_f32_16x16x32_bf16 v[108:111], v[146:149], v[170:173], v[108:111]
	v_mfma_f32_16x16x32_bf16 v[104:107], v[154:157], v[170:173], v[104:107]
	v_mfma_f32_16x16x32_bf16 v[92:95], v[146:149], v[178:181], v[92:95]
	v_mfma_f32_16x16x32_bf16 v[88:91], v[154:157], v[178:181], v[88:91]
	v_mfma_f32_16x16x32_bf16 v[76:79], v[146:149], v[186:189], v[76:79]
	v_mfma_f32_16x16x32_bf16 v[72:75], v[154:157], v[186:189], v[72:75]
	v_mfma_f32_16x16x32_bf16 v[124:127], v[150:153], v[166:169], v[124:127]
	v_mfma_f32_16x16x32_bf16 v[120:123], v[158:161], v[166:169], v[120:123]
	v_mfma_f32_16x16x32_bf16 v[108:111], v[150:153], v[174:177], v[108:111]
	v_mfma_f32_16x16x32_bf16 v[104:107], v[158:161], v[174:177], v[104:107]
	v_mfma_f32_16x16x32_bf16 v[92:95], v[150:153], v[182:185], v[92:95]
	v_mfma_f32_16x16x32_bf16 v[88:91], v[158:161], v[182:185], v[88:91]
	v_mfma_f32_16x16x32_bf16 v[76:79], v[150:153], v[190:193], v[76:79]
	v_mfma_f32_16x16x32_bf16 v[72:75], v[158:161], v[190:193], v[72:75]
	s_setprio 0
	s_setprio 1
	v_mfma_f32_16x16x32_bf16 v[116:119], v[130:133], v[162:165], v[116:119]
	v_mfma_f32_16x16x32_bf16 v[112:115], v[138:141], v[162:165], v[112:115]
	v_mfma_f32_16x16x32_bf16 v[100:103], v[130:133], v[170:173], v[100:103]
	v_mfma_f32_16x16x32_bf16 v[96:99], v[138:141], v[170:173], v[96:99]
	v_mfma_f32_16x16x32_bf16 v[84:87], v[130:133], v[178:181], v[84:87]
	v_mfma_f32_16x16x32_bf16 v[80:83], v[138:141], v[178:181], v[80:83]
	v_mfma_f32_16x16x32_bf16 v[68:71], v[130:133], v[186:189], v[68:71]
	v_mfma_f32_16x16x32_bf16 v[64:67], v[138:141], v[186:189], v[64:67]
	v_mfma_f32_16x16x32_bf16 v[116:119], v[134:137], v[166:169], v[116:119]
	v_mfma_f32_16x16x32_bf16 v[112:115], v[142:145], v[166:169], v[112:115]
	v_mfma_f32_16x16x32_bf16 v[100:103], v[134:137], v[174:177], v[100:103]
	v_mfma_f32_16x16x32_bf16 v[96:99], v[142:145], v[174:177], v[96:99]
	v_mfma_f32_16x16x32_bf16 v[84:87], v[134:137], v[182:185], v[84:87]
	v_mfma_f32_16x16x32_bf16 v[80:83], v[142:145], v[182:185], v[80:83]
	v_mfma_f32_16x16x32_bf16 v[68:71], v[134:137], v[190:193], v[68:71]
	v_mfma_f32_16x16x32_bf16 v[64:67], v[142:145], v[190:193], v[64:67]
	s_setprio 0
	s_barrier
	s_mov_b32 s38, m0
	s_mov_b32 m0, s67
	s_nop 0
	global_load_lds_dwordx4 v196, s[62:63]
	s_mov_b32 m0, s38
	ds_read_b128 v[186:189], v209 offset:16384
	ds_read_b128 v[190:193], v209 offset:17408
	s_add_u32 s44, s62, 0x40000
	s_mov_b32 s38, m0
	s_mov_b32 m0, s86
	s_nop 0
	global_load_lds_dwordx4 v198, s[62:63]
	s_mov_b32 m0, s38
	ds_read_b128 v[178:181], v209 offset:18432
	ds_read_b128 v[182:185], v209 offset:19456
	s_addc_u32 s45, s63, 0
	s_mov_b32 s38, m0
	s_mov_b32 m0, s87
	s_nop 0
	global_load_lds_dwordx4 v196, s[44:45]
	s_mov_b32 m0, s38
	ds_read_b128 v[170:173], v209 offset:20480
	ds_read_b128 v[174:177], v209 offset:21504
	v_cndmask_b32_e64 v128, 0, 1, s[72:73]
	s_mov_b32 s38, m0
	s_mov_b32 m0, s88
	s_nop 0
	global_load_lds_dwordx4 v198, s[44:45]
	s_mov_b32 m0, s38
	ds_read_b128 v[162:165], v209 offset:22528
	ds_read_b128 v[166:169], v209 offset:23552
	v_cmp_ne_u32_e64 s[44:45], 1, v128
	s_mov_b32 s38, m0
	s_mov_b32 m0, s51
	s_nop 0
	global_load_lds_dwordx4 v195, s[74:75]
	s_mov_b32 m0, s38
	s_andn2_b64 vcc, exec, s[72:73]
	s_mov_b32 s38, m0
	s_mov_b32 m0, s89
	s_nop 0
	global_load_lds_dwordx4 v197, s[74:75]
	s_mov_b32 m0, s38
	s_waitcnt vmcnt(8)
	s_waitcnt lgkmcnt(0)
	s_barrier
	s_cbranch_vccnz .LBB0_415
	s_setprio 1
	s_waitcnt lgkmcnt(0)
	v_mfma_f32_16x16x32_bf16 v[60:63], v[146:149], v[186:189], v[60:63]
	v_mfma_f32_16x16x32_bf16 v[56:59], v[154:157], v[186:189], v[56:59]
	v_mfma_f32_16x16x32_bf16 v[44:47], v[146:149], v[178:181], v[44:47]
	v_mfma_f32_16x16x32_bf16 v[40:43], v[154:157], v[178:181], v[40:43]
	v_mfma_f32_16x16x32_bf16 v[28:31], v[146:149], v[170:173], v[28:31]
	v_mfma_f32_16x16x32_bf16 v[24:27], v[154:157], v[170:173], v[24:27]
	v_mfma_f32_16x16x32_bf16 v[12:15], v[146:149], v[162:165], v[12:15]
	v_mfma_f32_16x16x32_bf16 v[8:11], v[154:157], v[162:165], v[8:11]
	v_mfma_f32_16x16x32_bf16 v[60:63], v[150:153], v[190:193], v[60:63]
	v_mfma_f32_16x16x32_bf16 v[56:59], v[158:161], v[190:193], v[56:59]
	v_mfma_f32_16x16x32_bf16 v[44:47], v[150:153], v[182:185], v[44:47]
	v_mfma_f32_16x16x32_bf16 v[40:43], v[158:161], v[182:185], v[40:43]
	v_mfma_f32_16x16x32_bf16 v[28:31], v[150:153], v[174:177], v[28:31]
	v_mfma_f32_16x16x32_bf16 v[24:27], v[158:161], v[174:177], v[24:27]
	v_mfma_f32_16x16x32_bf16 v[12:15], v[150:153], v[166:169], v[12:15]
	v_mfma_f32_16x16x32_bf16 v[8:11], v[158:161], v[166:169], v[8:11]
	s_setprio 0
	s_setprio 1
	v_mfma_f32_16x16x32_bf16 v[52:55], v[130:133], v[186:189], v[52:55]
	v_mfma_f32_16x16x32_bf16 v[48:51], v[138:141], v[186:189], v[48:51]
	v_mfma_f32_16x16x32_bf16 v[36:39], v[130:133], v[178:181], v[36:39]
	v_mfma_f32_16x16x32_bf16 v[32:35], v[138:141], v[178:181], v[32:35]
	v_mfma_f32_16x16x32_bf16 v[20:23], v[130:133], v[170:173], v[20:23]
	v_mfma_f32_16x16x32_bf16 v[16:19], v[138:141], v[170:173], v[16:19]
	v_mfma_f32_16x16x32_bf16 v[4:7], v[130:133], v[162:165], v[4:7]
	v_mfma_f32_16x16x32_bf16 v[0:3], v[138:141], v[162:165], v[0:3]
	v_mfma_f32_16x16x32_bf16 v[52:55], v[134:137], v[190:193], v[52:55]
	v_mfma_f32_16x16x32_bf16 v[48:51], v[142:145], v[190:193], v[48:51]
	v_mfma_f32_16x16x32_bf16 v[36:39], v[134:137], v[182:185], v[36:39]
	v_mfma_f32_16x16x32_bf16 v[32:35], v[142:145], v[182:185], v[32:35]
	v_mfma_f32_16x16x32_bf16 v[20:23], v[134:137], v[174:177], v[20:23]
	v_mfma_f32_16x16x32_bf16 v[16:19], v[142:145], v[174:177], v[16:19]
	v_mfma_f32_16x16x32_bf16 v[4:7], v[134:137], v[166:169], v[4:7]
	v_mfma_f32_16x16x32_bf16 v[0:3], v[142:145], v[166:169], v[0:3]
	s_setprio 0
.LBB0_415:
	s_add_u32 s76, s74, 0x80
	s_addc_u32 s77, s75, 0
	s_add_u32 s38, s62, 0x80
	s_addc_u32 s39, s63, 0
	s_barrier
	v_add_u32_e32 v128, 0x18000, v208
	ds_read_b128 v[146:149], v128
	ds_read_b128 v[150:153], v128 offset:1024
	ds_read_b128 v[154:157], v128 offset:2048
	ds_read_b128 v[158:161], v128 offset:3072
	v_add_u32_e32 v128, 0x1c000, v208
	ds_read_b128 v[130:133], v128
	ds_read_b128 v[134:137], v128 offset:1024
	ds_read_b128 v[138:141], v128 offset:2048
	ds_read_b128 v[142:145], v128 offset:3072
	s_waitcnt lgkmcnt(4)
	ds_read_b128 v[162:165], v209 offset:32768
	ds_read_b128 v[166:169], v209 offset:33792
	ds_read_b128 v[170:173], v209 offset:34816
	ds_read_b128 v[174:177], v209 offset:35840
	ds_read_b128 v[178:181], v209 offset:36864
	ds_read_b128 v[182:185], v209 offset:37888
	ds_read_b128 v[186:189], v209 offset:38912
	ds_read_b128 v[190:193], v209 offset:39936
	s_add_u32 s74, s74, 0x40000
	s_addc_u32 s75, s75, 0
	s_mov_b32 vcc_lo, m0
	s_mov_b32 m0, s92
	s_nop 0
	global_load_lds_dwordx4 v195, s[74:75]
	s_mov_b32 m0, vcc_lo
	s_nop 0
	s_mov_b32 vcc_lo, m0
	s_mov_b32 m0, s93
	s_nop 0
	global_load_lds_dwordx4 v197, s[74:75]
	s_mov_b32 m0, vcc_lo
	s_waitcnt vmcnt(8)
	s_waitcnt lgkmcnt(0)
	s_barrier
	s_setprio 1
	s_waitcnt lgkmcnt(0)
	v_mfma_f32_16x16x32_bf16 v[124:127], v[146:149], v[162:165], v[124:127]
	v_mfma_f32_16x16x32_bf16 v[120:123], v[154:157], v[162:165], v[120:123]
	v_mfma_f32_16x16x32_bf16 v[108:111], v[146:149], v[170:173], v[108:111]
	v_mfma_f32_16x16x32_bf16 v[104:107], v[154:157], v[170:173], v[104:107]
	v_mfma_f32_16x16x32_bf16 v[92:95], v[146:149], v[178:181], v[92:95]
	v_mfma_f32_16x16x32_bf16 v[88:91], v[154:157], v[178:181], v[88:91]
	v_mfma_f32_16x16x32_bf16 v[76:79], v[146:149], v[186:189], v[76:79]
	v_mfma_f32_16x16x32_bf16 v[72:75], v[154:157], v[186:189], v[72:75]
	v_mfma_f32_16x16x32_bf16 v[124:127], v[150:153], v[166:169], v[124:127]
	v_mfma_f32_16x16x32_bf16 v[120:123], v[158:161], v[166:169], v[120:123]
	v_mfma_f32_16x16x32_bf16 v[108:111], v[150:153], v[174:177], v[108:111]
	v_mfma_f32_16x16x32_bf16 v[104:107], v[158:161], v[174:177], v[104:107]
	v_mfma_f32_16x16x32_bf16 v[92:95], v[150:153], v[182:185], v[92:95]
	v_mfma_f32_16x16x32_bf16 v[88:91], v[158:161], v[182:185], v[88:91]
	v_mfma_f32_16x16x32_bf16 v[76:79], v[150:153], v[190:193], v[76:79]
	v_mfma_f32_16x16x32_bf16 v[72:75], v[158:161], v[190:193], v[72:75]
	s_setprio 0
	s_setprio 1
	v_mfma_f32_16x16x32_bf16 v[116:119], v[130:133], v[162:165], v[116:119]
	v_mfma_f32_16x16x32_bf16 v[112:115], v[138:141], v[162:165], v[112:115]
	v_mfma_f32_16x16x32_bf16 v[100:103], v[130:133], v[170:173], v[100:103]
	v_mfma_f32_16x16x32_bf16 v[96:99], v[138:141], v[170:173], v[96:99]
	v_mfma_f32_16x16x32_bf16 v[84:87], v[130:133], v[178:181], v[84:87]
	v_mfma_f32_16x16x32_bf16 v[80:83], v[138:141], v[178:181], v[80:83]
	v_mfma_f32_16x16x32_bf16 v[68:71], v[130:133], v[186:189], v[68:71]
	v_mfma_f32_16x16x32_bf16 v[64:67], v[138:141], v[186:189], v[64:67]
	v_mfma_f32_16x16x32_bf16 v[116:119], v[134:137], v[166:169], v[116:119]
	v_mfma_f32_16x16x32_bf16 v[112:115], v[142:145], v[166:169], v[112:115]
	v_mfma_f32_16x16x32_bf16 v[100:103], v[134:137], v[174:177], v[100:103]
	v_mfma_f32_16x16x32_bf16 v[96:99], v[142:145], v[174:177], v[96:99]
	v_mfma_f32_16x16x32_bf16 v[84:87], v[134:137], v[182:185], v[84:87]
	v_mfma_f32_16x16x32_bf16 v[80:83], v[142:145], v[182:185], v[80:83]
	v_mfma_f32_16x16x32_bf16 v[68:71], v[134:137], v[190:193], v[68:71]
	v_mfma_f32_16x16x32_bf16 v[64:67], v[142:145], v[190:193], v[64:67]
	s_setprio 0
	s_barrier
	s_mov_b32 s74, m0
	s_mov_b32 m0, s95
	s_nop 0
	global_load_lds_dwordx4 v196, s[38:39]
	s_mov_b32 m0, s74
	ds_read_b128 v[186:189], v209 offset:49152
	ds_read_b128 v[190:193], v209 offset:50176
	s_nop 0
	s_mov_b32 s74, m0
	s_mov_b32 m0, s96
	s_nop 0
	global_load_lds_dwordx4 v198, s[38:39]
	s_mov_b32 m0, s74
	ds_read_b128 v[178:181], v209 offset:51200
	ds_read_b128 v[182:185], v209 offset:52224
	s_add_u32 s38, s62, 0x40080
	s_addc_u32 s39, s63, 0
	s_mov_b32 s62, m0
	s_mov_b32 m0, s65
	s_nop 0
	global_load_lds_dwordx4 v196, s[38:39]
	s_mov_b32 m0, s62
	ds_read_b128 v[170:173], v209 offset:53248
	ds_read_b128 v[174:177], v209 offset:54272
	s_and_b64 vcc, exec, s[44:45]
	s_mov_b32 s62, m0
	s_mov_b32 m0, s50
	s_nop 0
	global_load_lds_dwordx4 v198, s[38:39]
	s_mov_b32 m0, s62
	ds_read_b128 v[162:165], v209 offset:55296
	ds_read_b128 v[166:169], v209 offset:56320
	s_mov_b32 s38, m0
	s_mov_b32 m0, s97
	s_nop 0
	global_load_lds_dwordx4 v195, s[76:77]
	s_mov_b32 m0, s38
	s_nop 0
	s_mov_b32 s38, m0
	s_mov_b32 m0, s9
	s_nop 0
	global_load_lds_dwordx4 v197, s[76:77]
	s_mov_b32 m0, s38
	s_waitcnt vmcnt(8)
	s_waitcnt lgkmcnt(0)
	s_barrier
	s_cbranch_vccnz .LBB0_412
	s_setprio 1
	s_waitcnt lgkmcnt(0)
	v_mfma_f32_16x16x32_bf16 v[60:63], v[146:149], v[186:189], v[60:63]
	v_mfma_f32_16x16x32_bf16 v[56:59], v[154:157], v[186:189], v[56:59]
	v_mfma_f32_16x16x32_bf16 v[44:47], v[146:149], v[178:181], v[44:47]
	v_mfma_f32_16x16x32_bf16 v[40:43], v[154:157], v[178:181], v[40:43]
	v_mfma_f32_16x16x32_bf16 v[28:31], v[146:149], v[170:173], v[28:31]
	v_mfma_f32_16x16x32_bf16 v[24:27], v[154:157], v[170:173], v[24:27]
	v_mfma_f32_16x16x32_bf16 v[12:15], v[146:149], v[162:165], v[12:15]
	v_mfma_f32_16x16x32_bf16 v[8:11], v[154:157], v[162:165], v[8:11]
	v_mfma_f32_16x16x32_bf16 v[60:63], v[150:153], v[190:193], v[60:63]
	v_mfma_f32_16x16x32_bf16 v[56:59], v[158:161], v[190:193], v[56:59]
	v_mfma_f32_16x16x32_bf16 v[44:47], v[150:153], v[182:185], v[44:47]
	v_mfma_f32_16x16x32_bf16 v[40:43], v[158:161], v[182:185], v[40:43]
	v_mfma_f32_16x16x32_bf16 v[28:31], v[150:153], v[174:177], v[28:31]
	v_mfma_f32_16x16x32_bf16 v[24:27], v[158:161], v[174:177], v[24:27]
	v_mfma_f32_16x16x32_bf16 v[12:15], v[150:153], v[166:169], v[12:15]
	v_mfma_f32_16x16x32_bf16 v[8:11], v[158:161], v[166:169], v[8:11]
	s_setprio 0
	s_setprio 1
	v_mfma_f32_16x16x32_bf16 v[52:55], v[130:133], v[186:189], v[52:55]
	v_mfma_f32_16x16x32_bf16 v[48:51], v[138:141], v[186:189], v[48:51]
	v_mfma_f32_16x16x32_bf16 v[36:39], v[130:133], v[178:181], v[36:39]
	v_mfma_f32_16x16x32_bf16 v[32:35], v[138:141], v[178:181], v[32:35]
	v_mfma_f32_16x16x32_bf16 v[20:23], v[130:133], v[170:173], v[20:23]
	v_mfma_f32_16x16x32_bf16 v[16:19], v[138:141], v[170:173], v[16:19]
	v_mfma_f32_16x16x32_bf16 v[4:7], v[130:133], v[162:165], v[4:7]
	v_mfma_f32_16x16x32_bf16 v[0:3], v[138:141], v[162:165], v[0:3]
	v_mfma_f32_16x16x32_bf16 v[52:55], v[134:137], v[190:193], v[52:55]
	v_mfma_f32_16x16x32_bf16 v[48:51], v[142:145], v[190:193], v[48:51]
	v_mfma_f32_16x16x32_bf16 v[36:39], v[134:137], v[182:185], v[36:39]
	v_mfma_f32_16x16x32_bf16 v[32:35], v[142:145], v[182:185], v[32:35]
	v_mfma_f32_16x16x32_bf16 v[20:23], v[134:137], v[174:177], v[20:23]
	v_mfma_f32_16x16x32_bf16 v[16:19], v[142:145], v[174:177], v[16:19]
	v_mfma_f32_16x16x32_bf16 v[4:7], v[134:137], v[166:169], v[4:7]
	v_mfma_f32_16x16x32_bf16 v[0:3], v[142:145], v[166:169], v[0:3]
	s_setprio 0
	s_branch .LBB0_412
